# diff block: V^T fragments read once per key half-tile and shared by both softmax maps (16 fewer ds_read_b64_tr per wave-tile); QK K-fragments moved to free v208-v215
# speedup vs baseline: 1.0169x; 1.0090x over previous
; #define LAS __attribute__((address_space(3)))
; #define MFMA32(a, b, c) __builtin_amdgcn_mfma_f32_32x32x16_bf16((a), (b), (c), 0, 0, 0)
; DI float fexp2(float x) { return __builtin_amdgcn_exp2f(x); }
; DI f32x16 zero16() { f32x16 z; for (int i = 0; i < 16; ++i) z[i] = 0.f; return z; }
; template <int MODE>
; DI void dense256_unit(const Params& p, int l, int b, int nq, int hd, LAS unsigned char* lds) {
;     ...
;       for (int mt = 0; mt < 2; ++mt) {
;         LAS unsigned char* krow = kt + (32 * mt + r) * W_RS + (8 * h) * 2;
;         const bf16x8 a0 = *(const LAS bf16x8*)(krow), a1 = *(const LAS bf16x8*)(krow + 32), a2 = *(const LAS bf16x8*)(krow + 64), a3 = *(const LAS bf16x8*)(krow + 96);
;         if (MODE == 0) {
;           f32x16 s1 = zero16(), s2 = zero16();
;           s1 = MFMA32(a0, qf[0], s1); s1 = MFMA32(a1, qf[1], s1); s2 = MFMA32(a2, qf[2], s2); s2 = MFMA32(a3, qf[3], s2);
; #pragma unroll
;           for (int i = 0; i < 16; ++i) { s1[i] = fexp2(s1[i]); l1 += s1[i]; s2[i] = fexp2(s2[i]); l2 += s2[i]; }
; #pragma unroll
;           for (int s = 0; s < 2; ++s) {
;             const bf16x8 p1 = pack8(s1, s), p2 = pack8(s2, s);
; #pragma unroll
;             for (int et = 0; et < 2; ++et) { const bf16x8 vf = vfrag144(vt, 32 * mt + 16 * s + 4 * h, 32 * et, lane); o1[et] = MFMA32(vf, p1, o1[et]); o2[et] = MFMA32(vf, p2, o2[et]); }
;           }
.LBB0_973:
	s_cmp_eq_u32 s13, 0
	s_cbranch_scc0 .Lmy_diff_buf1
	ds_read_b128 v[208:211], v192
	ds_read_b128 v[212:215], v192 offset:32
	s_waitcnt lgkmcnt(1)
	v_mfma_f32_32x32x16_bf16 v[66:81], v[208:211], v[114:117], 0
	ds_read_b128 v[208:211], v192 offset:64
	s_waitcnt lgkmcnt(1)
	v_mfma_f32_32x32x16_bf16 v[66:81], v[212:215], v[106:109], v[66:81]
	ds_read_b128 v[212:215], v192 offset:96
	s_nop 10
	s_waitcnt lgkmcnt(1)
	v_mfma_f32_32x32x16_bf16 v[82:97], v[208:211], v[110:113], 0
	ds_read_b128 v[208:211], v192 offset:4608
	v_exp_f32_e32 v66, v66
	v_exp_f32_e32 v67, v67
	v_exp_f32_e32 v68, v68
	v_exp_f32_e32 v69, v69
	v_exp_f32_e32 v70, v70
	v_exp_f32_e32 v71, v71
	v_exp_f32_e32 v72, v72
	v_exp_f32_e32 v73, v73
	v_add_f32_e32 v151, v151, v66
	v_add_f32_e32 v151, v151, v67
	v_add_f32_e32 v151, v151, v68
	v_add_f32_e32 v151, v151, v69
	v_exp_f32_e32 v74, v74
	v_exp_f32_e32 v75, v75
	v_exp_f32_e32 v76, v76
	v_exp_f32_e32 v77, v77
	v_exp_f32_e32 v78, v78
	v_exp_f32_e32 v79, v79
	v_exp_f32_e32 v80, v80
	v_exp_f32_e32 v81, v81
	s_waitcnt lgkmcnt(1)
	v_mfma_f32_32x32x16_bf16 v[82:97], v[212:215], v[118:121], v[82:97]
	ds_read_b128 v[212:215], v192 offset:4640
	v_add_f32_e32 v151, v151, v70
	v_add_f32_e32 v151, v151, v71
	v_add_f32_e32 v151, v151, v72
	v_add_f32_e32 v151, v151, v73
	v_add_f32_e32 v151, v151, v74
	v_add_f32_e32 v151, v151, v75
	v_add_f32_e32 v151, v151, v76
	v_add_f32_e32 v151, v151, v77
	v_add_f32_e32 v151, v151, v78
	v_add_f32_e32 v151, v151, v79
	v_add_f32_e32 v151, v151, v80
	v_add_f32_e32 v151, v151, v81
	v_cvt_pk_bf16_f32 v138, v66, v67
	v_cvt_pk_bf16_f32 v139, v68, v69
	v_cvt_pk_bf16_f32 v140, v70, v71
	v_cvt_pk_bf16_f32 v141, v72, v73
	v_cvt_pk_bf16_f32 v142, v74, v75
	v_cvt_pk_bf16_f32 v143, v76, v77
	v_cvt_pk_bf16_f32 v144, v78, v79
	v_cvt_pk_bf16_f32 v145, v80, v81
	ds_read_b64_tr_b16 v[164:165], v193 offset:18432
	ds_read_b64_tr_b16 v[166:167], v193 offset:19584
	ds_read_b64_tr_b16 v[124:125], v193 offset:18496
	ds_read_b64_tr_b16 v[126:127], v193 offset:19648
	ds_read_b64_tr_b16 v[156:157], v193 offset:20736
	ds_read_b64_tr_b16 v[158:159], v193 offset:21888
	ds_read_b64_tr_b16 v[160:161], v193 offset:20800
	ds_read_b64_tr_b16 v[162:163], v193 offset:21952
	s_waitcnt lgkmcnt(9)
	v_mfma_f32_32x32x16_bf16 v[66:81], v[208:211], v[114:117], 0
	ds_read_b128 v[208:211], v192 offset:4672
	v_exp_f32_e32 v82, v82
	v_exp_f32_e32 v83, v83
	v_exp_f32_e32 v84, v84
	v_exp_f32_e32 v85, v85
	v_exp_f32_e32 v86, v86
	v_exp_f32_e32 v87, v87
	s_waitcnt lgkmcnt(9)
	v_mfma_f32_32x32x16_bf16 v[66:81], v[212:215], v[106:109], v[66:81]
	ds_read_b128 v[212:215], v192 offset:4704
	v_exp_f32_e32 v88, v88
	v_exp_f32_e32 v89, v89
	v_add_f32_e32 v150, v150, v82
	v_add_f32_e32 v150, v150, v83
	v_add_f32_e32 v150, v150, v84
	v_add_f32_e32 v150, v150, v85
	s_waitcnt lgkmcnt(8)
	v_mfma_f32_32x32x16_bf16 v[34:49], v[164:167], v[138:141], v[34:49]
	v_exp_f32_e32 v90, v90
	v_exp_f32_e32 v91, v91
	v_exp_f32_e32 v92, v92
	v_exp_f32_e32 v93, v93
	v_exp_f32_e32 v94, v94
	v_exp_f32_e32 v95, v95
	s_waitcnt lgkmcnt(6)
	v_mfma_f32_32x32x16_bf16 v[2:17], v[124:127], v[138:141], v[2:17]
	v_exp_f32_e32 v96, v96
	v_exp_f32_e32 v97, v97
	v_add_f32_e32 v150, v150, v86
	v_add_f32_e32 v150, v150, v87
	v_add_f32_e32 v150, v150, v88
	v_add_f32_e32 v150, v150, v89
	s_waitcnt lgkmcnt(4)
	v_mfma_f32_32x32x16_bf16 v[34:49], v[156:159], v[142:145], v[34:49]
	v_add_f32_e32 v150, v150, v90
	v_add_f32_e32 v150, v150, v91
	v_add_f32_e32 v150, v150, v92
	v_add_f32_e32 v150, v150, v93
	v_add_f32_e32 v150, v150, v94
	v_add_f32_e32 v150, v150, v95
	s_waitcnt lgkmcnt(2)
	v_mfma_f32_32x32x16_bf16 v[2:17], v[160:163], v[142:145], v[2:17]
	v_add_f32_e32 v150, v150, v96
	v_add_f32_e32 v150, v150, v97
	v_cvt_pk_bf16_f32 v146, v82, v83
	v_cvt_pk_bf16_f32 v147, v84, v85
	v_cvt_pk_bf16_f32 v148, v86, v87
	v_cvt_pk_bf16_f32 v149, v88, v89
	v_cvt_pk_bf16_f32 v152, v90, v91
	v_cvt_pk_bf16_f32 v153, v92, v93
	v_cvt_pk_bf16_f32 v154, v94, v95
	v_cvt_pk_bf16_f32 v155, v96, v97
	s_waitcnt lgkmcnt(1)
	v_mfma_f32_32x32x16_bf16 v[82:97], v[208:211], v[110:113], 0
	v_exp_f32_e32 v66, v66
	v_exp_f32_e32 v67, v67
	v_exp_f32_e32 v68, v68
	v_exp_f32_e32 v69, v69
	v_exp_f32_e32 v70, v70
	v_exp_f32_e32 v71, v71
	s_waitcnt lgkmcnt(0)
	v_mfma_f32_32x32x16_bf16 v[82:97], v[212:215], v[118:121], v[82:97]
	v_exp_f32_e32 v72, v72
	v_exp_f32_e32 v73, v73
	v_add_f32_e32 v151, v151, v66
	v_add_f32_e32 v151, v151, v67
	v_add_f32_e32 v151, v151, v68
	v_add_f32_e32 v151, v151, v69
	v_mfma_f32_32x32x16_bf16 v[50:65], v[164:167], v[146:149], v[50:65]
	v_exp_f32_e32 v74, v74
	v_exp_f32_e32 v75, v75
	v_exp_f32_e32 v76, v76
	v_exp_f32_e32 v77, v77
	v_exp_f32_e32 v78, v78
	v_exp_f32_e32 v79, v79
	v_mfma_f32_32x32x16_bf16 v[18:33], v[124:127], v[146:149], v[18:33]
	v_exp_f32_e32 v80, v80
	v_exp_f32_e32 v81, v81
	v_add_f32_e32 v151, v151, v70
	v_add_f32_e32 v151, v151, v71
	v_add_f32_e32 v151, v151, v72
	v_add_f32_e32 v151, v151, v73
	v_mfma_f32_32x32x16_bf16 v[50:65], v[156:159], v[152:155], v[50:65]
	v_add_f32_e32 v151, v151, v74
	v_add_f32_e32 v151, v151, v75
	v_add_f32_e32 v151, v151, v76
	v_add_f32_e32 v151, v151, v77
	v_add_f32_e32 v151, v151, v78
	v_add_f32_e32 v151, v151, v79
	v_mfma_f32_32x32x16_bf16 v[18:33], v[160:163], v[152:155], v[18:33]
	v_add_f32_e32 v151, v151, v80
	v_add_f32_e32 v151, v151, v81
	v_cvt_pk_bf16_f32 v138, v66, v67
	v_cvt_pk_bf16_f32 v139, v68, v69
	v_cvt_pk_bf16_f32 v140, v70, v71
	v_cvt_pk_bf16_f32 v141, v72, v73
	v_cvt_pk_bf16_f32 v142, v74, v75
	v_cvt_pk_bf16_f32 v143, v76, v77
	v_cvt_pk_bf16_f32 v144, v78, v79
	v_cvt_pk_bf16_f32 v145, v80, v81
	ds_read_b64_tr_b16 v[164:165], v193 offset:23040
	ds_read_b64_tr_b16 v[166:167], v193 offset:24192
	ds_read_b64_tr_b16 v[124:125], v193 offset:23104
	ds_read_b64_tr_b16 v[126:127], v193 offset:24256
	ds_read_b64_tr_b16 v[156:157], v193 offset:25344
	ds_read_b64_tr_b16 v[158:159], v193 offset:26496
	ds_read_b64_tr_b16 v[160:161], v193 offset:25408
	ds_read_b64_tr_b16 v[162:163], v193 offset:26560
	s_waitcnt lgkmcnt(6)
; #define LAS __attribute__((address_space(3)))
; #define MFMA32(a, b, c) __builtin_amdgcn_mfma_f32_32x32x16_bf16((a), (b), (c), 0, 0, 0)
; DI float fexp2(float x) { return __builtin_amdgcn_exp2f(x); }
; DI f32x16 zero16() { f32x16 z; for (int i = 0; i < 16; ++i) z[i] = 0.f; return z; }
; template <int MODE>
; DI void dense256_unit(const Params& p, int l, int b, int nq, int hd, LAS unsigned char* lds) {
;     ...
;       for (int mt = 0; mt < 2; ++mt) {
;         LAS unsigned char* krow = kt + (32 * mt + r) * W_RS + (8 * h) * 2;
;         const bf16x8 a0 = *(const LAS bf16x8*)(krow), a1 = *(const LAS bf16x8*)(krow + 32), a2 = *(const LAS bf16x8*)(krow + 64), a3 = *(const LAS bf16x8*)(krow + 96);
;         if (MODE == 0) {
;           f32x16 s1 = zero16(), s2 = zero16();
;           s1 = MFMA32(a0, qf[0], s1); s1 = MFMA32(a1, qf[1], s1); s2 = MFMA32(a2, qf[2], s2); s2 = MFMA32(a3, qf[3], s2);
; #pragma unroll
;           for (int i = 0; i < 16; ++i) { s1[i] = fexp2(s1[i]); l1 += s1[i]; s2[i] = fexp2(s2[i]); l2 += s2[i]; }
; #pragma unroll
;           for (int s = 0; s < 2; ++s) {
;             const bf16x8 p1 = pack8(s1, s), p2 = pack8(s2, s);
; #pragma unroll
;             for (int et = 0; et < 2; ++et) { const bf16x8 vf = vfrag144(vt, 32 * mt + 16 * s + 4 * h, 32 * et, lane); o1[et] = MFMA32(vf, p1, o1[et]); o2[et] = MFMA32(vf, p2, o2[et]); }
;           }
	v_mfma_f32_32x32x16_bf16 v[34:49], v[164:167], v[138:141], v[34:49]
	v_exp_f32_e32 v82, v82
	v_exp_f32_e32 v83, v83
	v_exp_f32_e32 v84, v84
	v_exp_f32_e32 v85, v85
	v_exp_f32_e32 v86, v86
	v_exp_f32_e32 v87, v87
	v_exp_f32_e32 v88, v88
	v_exp_f32_e32 v89, v89
	v_add_f32_e32 v150, v150, v82
	v_add_f32_e32 v150, v150, v83
	s_waitcnt lgkmcnt(4)
	v_mfma_f32_32x32x16_bf16 v[2:17], v[124:127], v[138:141], v[2:17]
	v_add_f32_e32 v150, v150, v84
	v_add_f32_e32 v150, v150, v85
	v_exp_f32_e32 v90, v90
	v_exp_f32_e32 v91, v91
	v_exp_f32_e32 v92, v92
	v_exp_f32_e32 v93, v93
	v_exp_f32_e32 v94, v94
	v_exp_f32_e32 v95, v95
	v_exp_f32_e32 v96, v96
	v_exp_f32_e32 v97, v97
	s_waitcnt lgkmcnt(2)
	v_mfma_f32_32x32x16_bf16 v[34:49], v[156:159], v[142:145], v[34:49]
	v_add_f32_e32 v150, v150, v86
	v_add_f32_e32 v150, v150, v87
	v_add_f32_e32 v150, v150, v88
	v_add_f32_e32 v150, v150, v89
	v_add_f32_e32 v150, v150, v90
	v_add_f32_e32 v150, v150, v91
	v_add_f32_e32 v150, v150, v92
	v_add_f32_e32 v150, v150, v93
	v_add_f32_e32 v150, v150, v94
	v_add_f32_e32 v150, v150, v95
	s_waitcnt lgkmcnt(0)
	v_mfma_f32_32x32x16_bf16 v[2:17], v[160:163], v[142:145], v[2:17]
	v_add_f32_e32 v150, v150, v96
	v_add_f32_e32 v150, v150, v97
	v_cvt_pk_bf16_f32 v146, v82, v83
	v_cvt_pk_bf16_f32 v147, v84, v85
	v_cvt_pk_bf16_f32 v148, v86, v87
	v_cvt_pk_bf16_f32 v149, v88, v89
	v_cvt_pk_bf16_f32 v152, v90, v91
	v_cvt_pk_bf16_f32 v153, v92, v93
	v_cvt_pk_bf16_f32 v154, v94, v95
	v_cvt_pk_bf16_f32 v155, v96, v97
	v_mfma_f32_32x32x16_bf16 v[50:65], v[164:167], v[146:149], v[50:65]
	v_mfma_f32_32x32x16_bf16 v[18:33], v[124:127], v[146:149], v[18:33]
	v_mfma_f32_32x32x16_bf16 v[50:65], v[156:159], v[152:155], v[50:65]
	v_mfma_f32_32x32x16_bf16 v[18:33], v[160:163], v[152:155], v[18:33]
	s_branch .Lmy_diff_done
.Lmy_diff_buf1:
	ds_read_b128 v[208:211], v192 offset:9216
	ds_read_b128 v[212:215], v192 offset:9248
	s_waitcnt lgkmcnt(1)
	v_mfma_f32_32x32x16_bf16 v[66:81], v[208:211], v[114:117], 0
	ds_read_b128 v[208:211], v192 offset:9280
	s_waitcnt lgkmcnt(1)
	v_mfma_f32_32x32x16_bf16 v[66:81], v[212:215], v[106:109], v[66:81]
	ds_read_b128 v[212:215], v192 offset:9312
	s_nop 10
	s_waitcnt lgkmcnt(1)
	v_mfma_f32_32x32x16_bf16 v[82:97], v[208:211], v[110:113], 0
	ds_read_b128 v[208:211], v192 offset:13824
	v_exp_f32_e32 v66, v66
	v_exp_f32_e32 v67, v67
	v_exp_f32_e32 v68, v68
	v_exp_f32_e32 v69, v69
	v_exp_f32_e32 v70, v70
	v_exp_f32_e32 v71, v71
	v_exp_f32_e32 v72, v72
	v_exp_f32_e32 v73, v73
	v_add_f32_e32 v151, v151, v66
	v_add_f32_e32 v151, v151, v67
	v_add_f32_e32 v151, v151, v68
	v_add_f32_e32 v151, v151, v69
	v_exp_f32_e32 v74, v74
	v_exp_f32_e32 v75, v75
	v_exp_f32_e32 v76, v76
	v_exp_f32_e32 v77, v77
	v_exp_f32_e32 v78, v78
	v_exp_f32_e32 v79, v79
	v_exp_f32_e32 v80, v80
	v_exp_f32_e32 v81, v81
	s_waitcnt lgkmcnt(1)
	v_mfma_f32_32x32x16_bf16 v[82:97], v[212:215], v[118:121], v[82:97]
	ds_read_b128 v[212:215], v192 offset:13856
	v_add_f32_e32 v151, v151, v70
	v_add_f32_e32 v151, v151, v71
	v_add_f32_e32 v151, v151, v72
	v_add_f32_e32 v151, v151, v73
	v_add_f32_e32 v151, v151, v74
	v_add_f32_e32 v151, v151, v75
	v_add_f32_e32 v151, v151, v76
	v_add_f32_e32 v151, v151, v77
	v_add_f32_e32 v151, v151, v78
	v_add_f32_e32 v151, v151, v79
	v_add_f32_e32 v151, v151, v80
	v_add_f32_e32 v151, v151, v81
	v_cvt_pk_bf16_f32 v138, v66, v67
	v_cvt_pk_bf16_f32 v139, v68, v69
	v_cvt_pk_bf16_f32 v140, v70, v71
	v_cvt_pk_bf16_f32 v141, v72, v73
	v_cvt_pk_bf16_f32 v142, v74, v75
	v_cvt_pk_bf16_f32 v143, v76, v77
	v_cvt_pk_bf16_f32 v144, v78, v79
	v_cvt_pk_bf16_f32 v145, v80, v81
	ds_read_b64_tr_b16 v[164:165], v193 offset:27648
	ds_read_b64_tr_b16 v[166:167], v193 offset:28800
	ds_read_b64_tr_b16 v[124:125], v193 offset:27712
	ds_read_b64_tr_b16 v[126:127], v193 offset:28864
	ds_read_b64_tr_b16 v[156:157], v193 offset:29952
	ds_read_b64_tr_b16 v[158:159], v193 offset:31104
	ds_read_b64_tr_b16 v[160:161], v193 offset:30016
	ds_read_b64_tr_b16 v[162:163], v193 offset:31168
	s_waitcnt lgkmcnt(9)
	v_mfma_f32_32x32x16_bf16 v[66:81], v[208:211], v[114:117], 0
	ds_read_b128 v[208:211], v192 offset:13888
	v_exp_f32_e32 v82, v82
	v_exp_f32_e32 v83, v83
	v_exp_f32_e32 v84, v84
	v_exp_f32_e32 v85, v85
	v_exp_f32_e32 v86, v86
	v_exp_f32_e32 v87, v87
	s_waitcnt lgkmcnt(9)
	v_mfma_f32_32x32x16_bf16 v[66:81], v[212:215], v[106:109], v[66:81]
	ds_read_b128 v[212:215], v192 offset:13920
	v_exp_f32_e32 v88, v88
	v_exp_f32_e32 v89, v89
	v_add_f32_e32 v150, v150, v82
	v_add_f32_e32 v150, v150, v83
	v_add_f32_e32 v150, v150, v84
	v_add_f32_e32 v150, v150, v85
	s_waitcnt lgkmcnt(8)
	v_mfma_f32_32x32x16_bf16 v[34:49], v[164:167], v[138:141], v[34:49]
	v_exp_f32_e32 v90, v90
	v_exp_f32_e32 v91, v91
	v_exp_f32_e32 v92, v92
	v_exp_f32_e32 v93, v93
	v_exp_f32_e32 v94, v94
	v_exp_f32_e32 v95, v95
	s_waitcnt lgkmcnt(6)
; #define LAS __attribute__((address_space(3)))
; #define MFMA32(a, b, c) __builtin_amdgcn_mfma_f32_32x32x16_bf16((a), (b), (c), 0, 0, 0)
; DI float fexp2(float x) { return __builtin_amdgcn_exp2f(x); }
; DI f32x16 zero16() { f32x16 z; for (int i = 0; i < 16; ++i) z[i] = 0.f; return z; }
; template <int MODE>
; DI void dense256_unit(const Params& p, int l, int b, int nq, int hd, LAS unsigned char* lds) {
;     ...
;       for (int mt = 0; mt < 2; ++mt) {
;         LAS unsigned char* krow = kt + (32 * mt + r) * W_RS + (8 * h) * 2;
;         const bf16x8 a0 = *(const LAS bf16x8*)(krow), a1 = *(const LAS bf16x8*)(krow + 32), a2 = *(const LAS bf16x8*)(krow + 64), a3 = *(const LAS bf16x8*)(krow + 96);
;         if (MODE == 0) {
;           f32x16 s1 = zero16(), s2 = zero16();
;           s1 = MFMA32(a0, qf[0], s1); s1 = MFMA32(a1, qf[1], s1); s2 = MFMA32(a2, qf[2], s2); s2 = MFMA32(a3, qf[3], s2);
; #pragma unroll
;           for (int i = 0; i < 16; ++i) { s1[i] = fexp2(s1[i]); l1 += s1[i]; s2[i] = fexp2(s2[i]); l2 += s2[i]; }
; #pragma unroll
;           for (int s = 0; s < 2; ++s) {
;             const bf16x8 p1 = pack8(s1, s), p2 = pack8(s2, s);
; #pragma unroll
;             for (int et = 0; et < 2; ++et) { const bf16x8 vf = vfrag144(vt, 32 * mt + 16 * s + 4 * h, 32 * et, lane); o1[et] = MFMA32(vf, p1, o1[et]); o2[et] = MFMA32(vf, p2, o2[et]); }
;           }
	v_mfma_f32_32x32x16_bf16 v[2:17], v[124:127], v[138:141], v[2:17]
	v_exp_f32_e32 v96, v96
	v_exp_f32_e32 v97, v97
	v_add_f32_e32 v150, v150, v86
	v_add_f32_e32 v150, v150, v87
	v_add_f32_e32 v150, v150, v88
	v_add_f32_e32 v150, v150, v89
	s_waitcnt lgkmcnt(4)
	v_mfma_f32_32x32x16_bf16 v[34:49], v[156:159], v[142:145], v[34:49]
	v_add_f32_e32 v150, v150, v90
	v_add_f32_e32 v150, v150, v91
	v_add_f32_e32 v150, v150, v92
	v_add_f32_e32 v150, v150, v93
	v_add_f32_e32 v150, v150, v94
	v_add_f32_e32 v150, v150, v95
	s_waitcnt lgkmcnt(2)
	v_mfma_f32_32x32x16_bf16 v[2:17], v[160:163], v[142:145], v[2:17]
	v_add_f32_e32 v150, v150, v96
	v_add_f32_e32 v150, v150, v97
	v_cvt_pk_bf16_f32 v146, v82, v83
	v_cvt_pk_bf16_f32 v147, v84, v85
	v_cvt_pk_bf16_f32 v148, v86, v87
	v_cvt_pk_bf16_f32 v149, v88, v89
	v_cvt_pk_bf16_f32 v152, v90, v91
	v_cvt_pk_bf16_f32 v153, v92, v93
	v_cvt_pk_bf16_f32 v154, v94, v95
	v_cvt_pk_bf16_f32 v155, v96, v97
	s_waitcnt lgkmcnt(1)
	v_mfma_f32_32x32x16_bf16 v[82:97], v[208:211], v[110:113], 0
	v_exp_f32_e32 v66, v66
	v_exp_f32_e32 v67, v67
	v_exp_f32_e32 v68, v68
	v_exp_f32_e32 v69, v69
	v_exp_f32_e32 v70, v70
	v_exp_f32_e32 v71, v71
	s_waitcnt lgkmcnt(0)
	v_mfma_f32_32x32x16_bf16 v[82:97], v[212:215], v[118:121], v[82:97]
	v_exp_f32_e32 v72, v72
	v_exp_f32_e32 v73, v73
	v_add_f32_e32 v151, v151, v66
	v_add_f32_e32 v151, v151, v67
	v_add_f32_e32 v151, v151, v68
	v_add_f32_e32 v151, v151, v69
	v_mfma_f32_32x32x16_bf16 v[50:65], v[164:167], v[146:149], v[50:65]
	v_exp_f32_e32 v74, v74
	v_exp_f32_e32 v75, v75
	v_exp_f32_e32 v76, v76
	v_exp_f32_e32 v77, v77
	v_exp_f32_e32 v78, v78
	v_exp_f32_e32 v79, v79
	v_mfma_f32_32x32x16_bf16 v[18:33], v[124:127], v[146:149], v[18:33]
	v_exp_f32_e32 v80, v80
	v_exp_f32_e32 v81, v81
	v_add_f32_e32 v151, v151, v70
	v_add_f32_e32 v151, v151, v71
	v_add_f32_e32 v151, v151, v72
	v_add_f32_e32 v151, v151, v73
	v_mfma_f32_32x32x16_bf16 v[50:65], v[156:159], v[152:155], v[50:65]
	v_add_f32_e32 v151, v151, v74
	v_add_f32_e32 v151, v151, v75
	v_add_f32_e32 v151, v151, v76
	v_add_f32_e32 v151, v151, v77
	v_add_f32_e32 v151, v151, v78
	v_add_f32_e32 v151, v151, v79
	v_mfma_f32_32x32x16_bf16 v[18:33], v[160:163], v[152:155], v[18:33]
	v_add_f32_e32 v151, v151, v80
	v_add_f32_e32 v151, v151, v81
	v_cvt_pk_bf16_f32 v138, v66, v67
	v_cvt_pk_bf16_f32 v139, v68, v69
	v_cvt_pk_bf16_f32 v140, v70, v71
	v_cvt_pk_bf16_f32 v141, v72, v73
	v_cvt_pk_bf16_f32 v142, v74, v75
	v_cvt_pk_bf16_f32 v143, v76, v77
	v_cvt_pk_bf16_f32 v144, v78, v79
	v_cvt_pk_bf16_f32 v145, v80, v81
	ds_read_b64_tr_b16 v[164:165], v193 offset:32256
	ds_read_b64_tr_b16 v[166:167], v193 offset:33408
	ds_read_b64_tr_b16 v[124:125], v193 offset:32320
	ds_read_b64_tr_b16 v[126:127], v193 offset:33472
	ds_read_b64_tr_b16 v[156:157], v193 offset:34560
	ds_read_b64_tr_b16 v[158:159], v193 offset:35712
	ds_read_b64_tr_b16 v[160:161], v193 offset:34624
	ds_read_b64_tr_b16 v[162:163], v193 offset:35776
	s_waitcnt lgkmcnt(6)
	v_mfma_f32_32x32x16_bf16 v[34:49], v[164:167], v[138:141], v[34:49]
	v_exp_f32_e32 v82, v82
	v_exp_f32_e32 v83, v83
	v_exp_f32_e32 v84, v84
	v_exp_f32_e32 v85, v85
	v_exp_f32_e32 v86, v86
	v_exp_f32_e32 v87, v87
	v_exp_f32_e32 v88, v88
	v_exp_f32_e32 v89, v89
	v_add_f32_e32 v150, v150, v82
	v_add_f32_e32 v150, v150, v83
	s_waitcnt lgkmcnt(4)
	v_mfma_f32_32x32x16_bf16 v[2:17], v[124:127], v[138:141], v[2:17]
	v_add_f32_e32 v150, v150, v84
	v_add_f32_e32 v150, v150, v85
	v_exp_f32_e32 v90, v90
	v_exp_f32_e32 v91, v91
	v_exp_f32_e32 v92, v92
	v_exp_f32_e32 v93, v93
	v_exp_f32_e32 v94, v94
	v_exp_f32_e32 v95, v95
	v_exp_f32_e32 v96, v96
	v_exp_f32_e32 v97, v97
	s_waitcnt lgkmcnt(2)
	v_mfma_f32_32x32x16_bf16 v[34:49], v[156:159], v[142:145], v[34:49]
	v_add_f32_e32 v150, v150, v86
	v_add_f32_e32 v150, v150, v87
	v_add_f32_e32 v150, v150, v88
	v_add_f32_e32 v150, v150, v89
	v_add_f32_e32 v150, v150, v90
	v_add_f32_e32 v150, v150, v91
	v_add_f32_e32 v150, v150, v92
	v_add_f32_e32 v150, v150, v93
	v_add_f32_e32 v150, v150, v94
	v_add_f32_e32 v150, v150, v95
	s_waitcnt lgkmcnt(0)
	v_mfma_f32_32x32x16_bf16 v[2:17], v[160:163], v[142:145], v[2:17]
	v_add_f32_e32 v150, v150, v96
	v_add_f32_e32 v150, v150, v97
	v_cvt_pk_bf16_f32 v146, v82, v83
	v_cvt_pk_bf16_f32 v147, v84, v85
	v_cvt_pk_bf16_f32 v148, v86, v87
	v_cvt_pk_bf16_f32 v149, v88, v89
	v_cvt_pk_bf16_f32 v152, v90, v91
	v_cvt_pk_bf16_f32 v153, v92, v93
	v_cvt_pk_bf16_f32 v154, v94, v95
	v_cvt_pk_bf16_f32 v155, v96, v97
	v_mfma_f32_32x32x16_bf16 v[50:65], v[164:167], v[146:149], v[50:65]
	v_mfma_f32_32x32x16_bf16 v[18:33], v[124:127], v[146:149], v[18:33]
	v_mfma_f32_32x32x16_bf16 v[50:65], v[156:159], v[152:155], v[50:65]
	v_mfma_f32_32x32x16_bf16 v[18:33], v[160:163], v[152:155], v[18:33]
